# scan chunk loops rewritten: permlane32_swap lane exchange instead of LDS, transposed C*H^T MFMA with direct stores, software pipelined
# speedup vs baseline: 1.1195x; 1.0128x over previous
.LBB0_524:
	s_andn2_b64 vcc, exec, s[42:43]
	s_cbranch_vccnz .LBB0_704
	v_readlane_b32 s42, v253, 2
	v_readlane_b32 s43, v253, 3
	s_waitcnt lgkmcnt(0)
	s_load_dwordx8 s[52:59], s[42:43], 0xe0
	v_readlane_b32 s2, v254, 35
	v_writelane_b32 v255, s60, 0
	v_readlane_b32 s3, v254, 36
	v_mov_b32_e32 v0, v133
	v_writelane_b32 v255, s61, 1
	v_mov_b32_e32 v1, v133
	s_andn2_b64 vcc, exec, s[2:3]
	s_cbranch_vccnz .LBB0_633
	s_load_dwordx4 s[72:75], s[42:43], 0x10
	s_load_dwordx2 s[92:93], s[42:43], 0x98
	s_load_dwordx4 s[76:79], s[42:43], 0x88
	s_load_dwordx8 s[60:67], s[42:43], 0x68
	v_ashrrev_i32_e32 v119, 6, v1
	s_movk_i32 s2, 0x4200
	v_mul_lo_u32 v127, v119, s2
	v_readlane_b32 s2, v254, 60
	v_and_b32_e32 v2, 1, v0
	v_and_b32_e32 v124, 31, v0
	s_waitcnt lgkmcnt(0)
	s_add_u32 s94, s58, 0x22600000
	v_and_b32_e32 v1, 31, v0
	v_readlane_b32 s3, v254, 61
	v_cmp_eq_u32_e64 s[42:43], 0, v2
	v_lshrrev_b32_e32 v2, 3, v0
	v_lshlrev_b32_e32 v126, 4, v124
	v_and_b32_e32 v128, 32, v0
	v_readlane_b32 s38, v253, 0
	v_and_b32_e32 v118, 63, v0
	s_addc_u32 s95, s59, 0
	s_lshl_b32 s2, s2, 7
	v_cmp_gt_u32_e64 s[44:45], 16, v1
	v_and_b32_e32 v120, 4, v2
	v_lshlrev_b32_e32 v122, 6, v1
	v_mov_b32_e32 v123, v129
	s_mov_b32 s80, s40
	s_waitcnt vmcnt(3)
	v_mov_b32_e32 v130, v126
	v_or_b32_e32 v132, 0x200, v126
	v_or_b32_e32 v134, 0x200, v126
	v_mov_b32_e32 v121, v129
	v_lshl_add_u64 v[136:137], s[66:67], 0, v[128:129]
	v_lshl_add_u64 v[138:139], s[76:77], 0, v[128:129]
	v_mov_b32_e32 v125, v129
	s_mov_b32 s3, s38
	v_readlane_b32 s39, v253, 1
	s_branch .LBB0_528

.LBB0_536:
	s_or_b64 exec, exec, s[46:47]
	v_lshlrev_b64 v[62:63], 10, v[0:1]
	v_ashrrev_i32_e32 v5, 31, v4
	v_or_b32_e32 v0, v62, v126
	v_mov_b32_e32 v1, v63
	v_lshl_add_u64 v[4:5], v[4:5], 0, v[124:125]
	v_lshlrev_b64 v[0:1], 2, v[0:1]
	v_lshlrev_b64 v[16:17], 2, v[4:5]
	v_lshl_add_u64 v[6:7], v[136:137], 0, v[0:1]
	v_lshl_add_u64 v[12:13], v[138:139], 0, v[0:1]
	v_lshl_add_u64 v[36:37], s[62:63], 0, v[16:17]
	v_lshl_add_u64 v[48:49], s[60:61], 0, v[16:17]
	global_load_dwordx4 v[0:3], v[6:7], off offset:16
	global_load_dwordx4 v[8:11], v[6:7], off
	global_load_dword v99, v[36:37], off
	s_nop 0
	global_load_dwordx4 v[4:7], v[12:13], off offset:16
	s_nop 0
	global_load_dwordx4 v[12:15], v[12:13], off
	s_waitcnt vmcnt(2)
	v_mul_f32_e32 v108, v110, v99
	global_load_dword v98, v[48:49], off
	v_and_b32_e32 v109, 0x7fffffff, v108
	v_cmp_nlt_f32_e64 s[46:47], |v108|, s12
	s_and_saveexec_b64 s[48:49], s[46:47]
	s_xor_b64 s[96:97], exec, s[48:49]
	s_cbranch_execz .LBB0_538
	v_lshrrev_b32_e32 v16, 23, v109
	v_add_u32_e32 v16, 0xffffff88, v16
	v_cmp_lt_u32_e32 vcc, 63, v16
	s_mov_b32 s50, 0xfe5163ab
	s_nop 0
	v_cndmask_b32_e32 v17, 0, v187, vcc
	v_add_u32_e32 v16, v17, v16
	v_cmp_lt_u32_e64 s[46:47], 31, v16
	s_nop 1
	v_cndmask_b32_e64 v17, 0, v190, s[46:47]
	v_add_u32_e32 v16, v17, v16
	v_cmp_lt_u32_e64 s[48:49], 31, v16
	s_nop 1
	v_cndmask_b32_e64 v17, 0, v190, s[48:49]
	v_add_u32_e32 v30, v17, v16
	v_and_b32_e32 v16, 0x7fffff, v109
	v_or_b32_e32 v28, 0x800000, v16
	v_mad_u64_u32 v[16:17], s[50:51], v28, s50, 0
	v_mov_b32_e32 v128, v17
	s_mov_b32 s50, 0x3c439041
	v_mad_u64_u32 v[18:19], s[50:51], v28, s50, v[128:129]
	v_mov_b32_e32 v128, v19
	s_mov_b32 s50, 0xdb629599
	v_mad_u64_u32 v[20:21], s[50:51], v28, s50, v[128:129]
	v_mov_b32_e32 v128, v21
	s_mov_b32 s50, 0xf534ddc0
	v_mad_u64_u32 v[22:23], s[50:51], v28, s50, v[128:129]
	v_mov_b32_e32 v128, v23
	s_mov_b32 s50, 0xfc2757d1
	v_mad_u64_u32 v[24:25], s[50:51], v28, s50, v[128:129]
	v_mov_b32_e32 v128, v25
	s_mov_b32 s50, 0x4e441529
	v_mad_u64_u32 v[26:27], s[50:51], v28, s50, v[128:129]
	v_mov_b32_e32 v128, v27
	s_mov_b32 s50, 0xa2f9836e
	v_mad_u64_u32 v[28:29], s[50:51], v28, s50, v[128:129]
	v_cndmask_b32_e32 v17, v26, v22, vcc
	v_cndmask_b32_e32 v19, v28, v24, vcc
	v_cndmask_b32_e32 v23, v29, v26, vcc
	v_cndmask_b32_e64 v21, v19, v17, s[46:47]
	v_cndmask_b32_e64 v19, v23, v19, s[46:47]
	v_cndmask_b32_e32 v23, v24, v20, vcc
	v_cndmask_b32_e64 v17, v17, v23, s[46:47]
	v_cndmask_b32_e32 v18, v22, v18, vcc
	v_cndmask_b32_e64 v19, v19, v21, s[48:49]
	v_cndmask_b32_e64 v21, v21, v17, s[48:49]
	v_sub_u32_e32 v24, 32, v30
	v_cndmask_b32_e64 v22, v23, v18, s[46:47]
	v_alignbit_b32 v25, v19, v21, v24
	v_cmp_eq_u32_e64 s[50:51], 0, v30
	v_cndmask_b32_e64 v17, v17, v22, s[48:49]
	v_alignbit_b32 v23, v21, v17, v24
	v_cndmask_b32_e64 v19, v25, v19, s[50:51]
	v_cndmask_b32_e32 v16, v20, v16, vcc
	v_cndmask_b32_e64 v21, v23, v21, s[50:51]
	v_bfe_u32 v26, v19, 29, 1
	v_cndmask_b32_e64 v16, v18, v16, s[46:47]
	v_alignbit_b32 v23, v19, v21, 30
	v_sub_u32_e32 v27, 0, v26
	v_cndmask_b32_e64 v16, v22, v16, s[48:49]
	v_xor_b32_e32 v23, v23, v27
	v_alignbit_b32 v18, v17, v16, v24
	v_cndmask_b32_e64 v17, v18, v17, s[50:51]
	v_ffbh_u32_e32 v20, v23
	v_alignbit_b32 v18, v21, v17, 30
	v_min_u32_e32 v20, 32, v20
	v_alignbit_b32 v16, v17, v16, 30
	v_xor_b32_e32 v18, v18, v27
	v_sub_u32_e32 v21, 31, v20
	v_xor_b32_e32 v16, v16, v27
	v_alignbit_b32 v22, v23, v18, v21
	v_alignbit_b32 v16, v18, v16, v21
	v_alignbit_b32 v17, v22, v16, 9
	v_ffbh_u32_e32 v18, v17
	v_min_u32_e32 v18, 32, v18
	v_lshrrev_b32_e32 v25, 29, v19
	v_not_b32_e32 v21, v18
	v_alignbit_b32 v16, v17, v16, v21
	v_lshlrev_b32_e32 v17, 31, v25
	v_or_b32_e32 v21, 0x33000000, v17
	v_add_lshl_u32 v18, v18, v20, 23
	v_lshrrev_b32_e32 v16, 9, v16
	v_sub_u32_e32 v18, v21, v18
	v_or_b32_e32 v17, 0.5, v17
	v_lshlrev_b32_e32 v20, 23, v20
	v_or_b32_e32 v16, v18, v16
	v_lshrrev_b32_e32 v18, 9, v22
	v_sub_u32_e32 v17, v17, v20
	v_or_b32_e32 v17, v18, v17
	v_mul_f32_e32 v18, 0x3fc90fda, v17
	s_mov_b32 s46, 0x3fc90fda
	v_fma_f32 v20, v17, s46, -v18
	v_fmac_f32_e32 v20, 0x33a22168, v17
	v_fmac_f32_e32 v20, 0x3fc90fda, v16
	v_lshrrev_b32_e32 v16, 30, v19
	v_add_f32_e32 v116, v18, v20
	v_add_u32_e32 v117, v26, v16

.LBB0_544:
	s_or_b64 exec, exec, s[46:47]
	v_or_b32_e32 v32, v62, v132
	v_mov_b32_e32 v33, v63
	v_lshlrev_b64 v[32:33], 2, v[32:33]
	v_lshl_add_u64 v[38:39], v[136:137], 0, v[32:33]
	v_lshl_add_u64 v[44:45], v[138:139], 0, v[32:33]
	global_load_dwordx4 v[32:35], v[38:39], off offset:16
	global_load_dwordx4 v[40:43], v[38:39], off
	global_load_dword v105, v[36:37], off offset:128
	s_nop 0
	global_load_dwordx4 v[36:39], v[44:45], off offset:16
	s_nop 0
	global_load_dwordx4 v[44:47], v[44:45], off
	s_nop 0
	global_load_dword v104, v[48:49], off offset:128
	s_waitcnt vmcnt(3)
	v_mul_f32_e32 v146, v110, v105
	v_and_b32_e32 v147, 0x7fffffff, v146
	v_cmp_nlt_f32_e64 s[46:47], |v146|, s12
	s_and_saveexec_b64 s[48:49], s[46:47]
	s_xor_b64 s[96:97], exec, s[48:49]
	s_cbranch_execz .LBB0_546
	v_lshrrev_b32_e32 v48, 23, v147
	v_add_u32_e32 v48, 0xffffff88, v48
	v_cmp_lt_u32_e32 vcc, 63, v48
	s_mov_b32 s50, 0xfe5163ab
	s_nop 0
	v_cndmask_b32_e32 v49, 0, v187, vcc
	v_add_u32_e32 v48, v49, v48
	v_cmp_lt_u32_e64 s[46:47], 31, v48
	s_nop 1
	v_cndmask_b32_e64 v49, 0, v190, s[46:47]
	v_add_u32_e32 v48, v49, v48
	v_cmp_lt_u32_e64 s[48:49], 31, v48
	s_nop 1
	v_cndmask_b32_e64 v49, 0, v190, s[48:49]
	v_add_u32_e32 v64, v49, v48
	v_and_b32_e32 v48, 0x7fffff, v147
	v_or_b32_e32 v66, 0x800000, v48
	v_mad_u64_u32 v[48:49], s[50:51], v66, s50, 0
	v_mov_b32_e32 v128, v49
	s_mov_b32 s50, 0x3c439041
	v_mad_u64_u32 v[50:51], s[50:51], v66, s50, v[128:129]
	v_mov_b32_e32 v128, v51
	s_mov_b32 s50, 0xdb629599
	v_mad_u64_u32 v[52:53], s[50:51], v66, s50, v[128:129]
	v_mov_b32_e32 v128, v53
	s_mov_b32 s50, 0xf534ddc0
	v_mad_u64_u32 v[54:55], s[50:51], v66, s50, v[128:129]
	v_mov_b32_e32 v128, v55
	s_mov_b32 s50, 0xfc2757d1
	v_mad_u64_u32 v[56:57], s[50:51], v66, s50, v[128:129]
	v_mov_b32_e32 v128, v57
	s_mov_b32 s50, 0x4e441529
	v_mad_u64_u32 v[58:59], s[50:51], v66, s50, v[128:129]
	v_mov_b32_e32 v128, v59
	s_mov_b32 s50, 0xa2f9836e
	v_mad_u64_u32 v[66:67], s[50:51], v66, s50, v[128:129]
	v_cndmask_b32_e32 v49, v58, v54, vcc
	v_cndmask_b32_e32 v51, v66, v56, vcc
	v_cndmask_b32_e32 v55, v67, v58, vcc
	v_cndmask_b32_e64 v53, v51, v49, s[46:47]
	v_cndmask_b32_e64 v51, v55, v51, s[46:47]
	v_cndmask_b32_e32 v55, v56, v52, vcc
	v_cndmask_b32_e64 v49, v49, v55, s[46:47]
	v_cndmask_b32_e32 v50, v54, v50, vcc
	v_cndmask_b32_e64 v51, v51, v53, s[48:49]
	v_cndmask_b32_e64 v53, v53, v49, s[48:49]
	v_sub_u32_e32 v56, 32, v64
	v_cndmask_b32_e64 v54, v55, v50, s[46:47]
	v_alignbit_b32 v57, v51, v53, v56
	v_cmp_eq_u32_e64 s[50:51], 0, v64
	v_cndmask_b32_e64 v49, v49, v54, s[48:49]
	v_alignbit_b32 v55, v53, v49, v56
	v_cndmask_b32_e64 v51, v57, v51, s[50:51]
	v_cndmask_b32_e32 v48, v52, v48, vcc
	v_cndmask_b32_e64 v53, v55, v53, s[50:51]
	v_bfe_u32 v58, v51, 29, 1
	v_cndmask_b32_e64 v48, v50, v48, s[46:47]
	v_alignbit_b32 v55, v51, v53, 30
	v_sub_u32_e32 v59, 0, v58
	v_cndmask_b32_e64 v48, v54, v48, s[48:49]
	v_xor_b32_e32 v55, v55, v59
	v_alignbit_b32 v50, v49, v48, v56
	v_cndmask_b32_e64 v49, v50, v49, s[50:51]
	v_ffbh_u32_e32 v52, v55
	v_alignbit_b32 v50, v53, v49, 30
	v_min_u32_e32 v52, 32, v52
	v_alignbit_b32 v48, v49, v48, 30
	v_xor_b32_e32 v50, v50, v59
	v_sub_u32_e32 v53, 31, v52
	v_xor_b32_e32 v48, v48, v59
	v_alignbit_b32 v54, v55, v50, v53
	v_alignbit_b32 v48, v50, v48, v53
	v_alignbit_b32 v49, v54, v48, 9
	v_ffbh_u32_e32 v50, v49
	v_min_u32_e32 v50, 32, v50
	v_lshrrev_b32_e32 v57, 29, v51
	v_not_b32_e32 v53, v50
	v_alignbit_b32 v48, v49, v48, v53
	v_lshlrev_b32_e32 v49, 31, v57
	v_or_b32_e32 v53, 0x33000000, v49
	v_add_lshl_u32 v50, v50, v52, 23
	v_lshrrev_b32_e32 v48, 9, v48
	v_sub_u32_e32 v50, v53, v50
	v_or_b32_e32 v49, 0.5, v49
	v_lshlrev_b32_e32 v52, 23, v52
	v_or_b32_e32 v48, v50, v48
	v_lshrrev_b32_e32 v50, 9, v54
	v_sub_u32_e32 v49, v49, v52
	v_or_b32_e32 v49, v50, v49
	v_mul_f32_e32 v50, 0x3fc90fda, v49
	s_mov_b32 s46, 0x3fc90fda
	v_fma_f32 v52, v49, s46, -v50
	v_fmac_f32_e32 v52, 0x33a22168, v49
	v_fmac_f32_e32 v52, 0x3fc90fda, v48
	v_lshrrev_b32_e32 v48, 30, v51
	v_add_f32_e32 v128, v50, v52
	v_add_u32_e32 v148, v58, v48

.LBB0_615:
	s_waitcnt vmcnt(0)
	v_cvt_pk_bf16_f32 v87, v87, v92
	v_cvt_pk_bf16_f32 v92, v89, v90
	v_cvt_pk_bf16_f32 v89, v131, v150
	v_mul_f32_e32 v131, v100, v100
	v_cvt_pk_bf16_f32 v88, v88, v149
	v_fmamk_f32 v149, v131, 0xb94c1982, v180
	v_fmaak_f32 v149, v131, v149, 0xbe2aaa9d
	v_mul_f32_e32 v149, v131, v149
	v_fmac_f32_e32 v100, v100, v149
	v_fmamk_f32 v149, v131, 0x37d75334, v181
	v_fmaak_f32 v149, v131, v149, 0x3d2aabf7
	v_fmaak_f32 v149, v131, v149, 0xbf000004
	v_lshlrev_b32_e32 v150, 30, v115
	v_and_b32_e32 v115, 1, v115
	v_fma_f32 v149, v131, v149, 1.0
	v_cmp_eq_u32_e64 s[46:47], 0, v115
	v_mul_f32_e32 v65, v65, v110
	v_xor_b32_e32 v107, v107, v106
	v_cndmask_b32_e64 v115, v149, v100, s[46:47]
	v_mul_f32_e32 v65, 0x3fb8aa3b, v65
	v_xor_b32_e32 v107, v107, v115
	v_exp_f32_e32 v115, v65
	v_and_b32_e32 v131, 0x80000000, v150
	v_xor_b32_e32 v107, v107, v131
	v_cmp_class_f32_e64 s[48:49], v106, s10
	v_cvt_pk_bf16_f32 v82, v82, v151
	v_xor_b32_e32 v147, v147, v146
	v_cndmask_b32_e64 v106, v191, v107, s[48:49]
	v_mul_f32_e32 v131, v115, v106
	v_mul_f32_e32 v106, v110, v104
	v_mul_f32_e32 v106, 0x3fb8aa3b, v106
	v_exp_f32_e32 v107, v106
	v_mul_f32_e32 v106, v128, v128
	v_fmamk_f32 v151, v106, 0xb94c1982, v180
	v_fmaak_f32 v151, v106, v151, 0xbe2aaa9d
	v_mul_f32_e32 v151, v106, v151
	v_fmac_f32_e32 v128, v128, v151
	v_fmamk_f32 v151, v106, 0x37d75334, v181
	v_fmaak_f32 v151, v106, v151, 0x3d2aabf7
	v_fmaak_f32 v151, v106, v151, 0xbf000004
	v_fma_f32 v106, v106, v151, 1.0
	v_lshlrev_b32_e32 v151, 30, v148
	v_and_b32_e32 v148, 1, v148
	v_cmp_eq_u32_e32 vcc, 0, v148
	v_cvt_pk_bf16_f32 v83, v83, v152
	v_and_b32_e32 v152, 0x80000000, v151
	v_cndmask_b32_e32 v148, v106, v128, vcc
	v_xor_b32_e32 v128, 0x80000000, v128
	v_xor_b32_e32 v147, v147, v148
	v_cndmask_b32_e32 v106, v128, v106, vcc
	v_xor_b32_e32 v147, v147, v152
	v_bitop3_b32 v106, v106, v151, s14 bitop3:0x78
	v_cmp_class_f32_e64 vcc, v146, s10
	v_cvt_pk_bf16_f32 v64, v64, v198
	v_cvt_pk_bf16_f32 v63, v195, v197
	v_cndmask_b32_e32 v106, v191, v106, vcc
	v_cndmask_b32_e32 v128, v191, v147, vcc
	v_pk_mul_f32 v[146:147], v[104:105], v[104:105]
	v_fma_f32 v106, v107, v106, -1.0
	v_mul_f32_e32 v107, v107, v128
	v_add_f32_e32 v128, v146, v147
	v_div_scale_f32 v146, s[96:97], v128, v128, 1.0
	v_rcp_f32_e32 v147, v146
	v_cvt_pk_bf16_f32 v62, v194, v196
	v_cvt_pk_bf16_f32 v68, v68, v175
	v_cvt_pk_bf16_f32 v67, v67, v173
	v_fma_f32 v148, -v146, v147, 1.0
	v_fmac_f32_e32 v147, v148, v147
	v_div_scale_f32 v148, vcc, 1.0, v128, 1.0
	v_mul_f32_e32 v151, v148, v147
	v_fma_f32 v152, -v146, v151, v148
	v_fmac_f32_e32 v151, v152, v147
	v_fma_f32 v146, -v146, v151, v148
	v_div_fmas_f32 v146, v146, v147, v151
	v_div_fixup_f32 v148, v146, v128, 1.0
	v_pk_mul_f32 v[146:147], v[104:105], v[106:107]
	v_cvt_pk_bf16_f32 v66, v66, v171
	v_add_f32_e32 v128, v146, v147
	v_mov_b32_e32 v146, v107
	v_mov_b32_e32 v147, v106
	v_pk_mul_f32 v[104:105], v[104:105], v[146:147]
	v_mul_f32_e32 v128, v148, v128
	v_sub_f32_e32 v104, v104, v105
	v_mul_f32_e32 v104, v148, v104
	v_pk_mul_f32 v[106:107], v[94:95], v[128:129] op_sel_hi:[1,0]
	v_pk_mul_f32 v[94:95], v[94:95], v[104:105] op_sel_hi:[1,0]
	v_pk_fma_f32 v[106:107], v[56:57], v[104:105], v[106:107] op_sel_hi:[1,0,1]
	v_pk_fma_f32 v[56:57], v[56:57], v[128:129], v[94:95] op_sel_hi:[1,0,1] neg_lo:[0,0,1] neg_hi:[0,0,1]
	v_cvt_pk_bf16_f32 v72, v72, v170
	v_mov_b32_e32 v57, v107
	v_mov_b32_e32 v56, v106
	v_cvt_pk_bf16_f32 v94, v56, v57
	v_pk_mul_f32 v[56:57], v[96:97], v[128:129] op_sel_hi:[1,0]
	v_pk_mul_f32 v[96:97], v[96:97], v[104:105] op_sel_hi:[1,0]
	v_pk_fma_f32 v[56:57], v[58:59], v[104:105], v[56:57] op_sel_hi:[1,0,1]
	v_pk_fma_f32 v[58:59], v[58:59], v[128:129], v[96:97] op_sel_hi:[1,0,1] neg_lo:[0,0,1] neg_hi:[0,0,1]
	v_cvt_pk_bf16_f32 v71, v71, v168
	s_nop 0
	s_nop 0
	v_cvt_pk_bf16_f32 v95, v56, v57
	v_pk_mul_f32 v[56:57], v[52:53], v[128:129] op_sel_hi:[1,0]
	v_pk_mul_f32 v[52:53], v[52:53], v[104:105] op_sel_hi:[1,0]
	v_pk_fma_f32 v[56:57], v[48:49], v[104:105], v[56:57] op_sel_hi:[1,0,1]
	v_pk_fma_f32 v[48:49], v[48:49], v[128:129], v[52:53] op_sel_hi:[1,0,1] neg_lo:[0,0,1] neg_hi:[0,0,1]
	v_pk_mul_f32 v[52:53], v[104:105], v[54:55] op_sel_hi:[0,1]
	v_mov_b32_e32 v49, v57
	v_mov_b32_e32 v48, v56
	v_cvt_pk_bf16_f32 v96, v48, v49
	v_pk_mul_f32 v[48:49], v[128:129], v[54:55] op_sel_hi:[0,1]
	v_pk_fma_f32 v[48:49], v[50:51], v[104:105], v[48:49] op_sel_hi:[1,0,1]
	v_pk_fma_f32 v[50:51], v[50:51], v[128:129], v[52:53] op_sel_hi:[1,0,1] neg_lo:[0,0,1] neg_hi:[0,0,1]
	v_and_b32_e32 v52, 1, v145
	s_nop 0
	s_nop 0
	v_cvt_pk_bf16_f32 v97, v48, v49
	v_mul_f32_e32 v48, v110, v102
	v_mul_f32_e32 v48, 0x3fb8aa3b, v48
	v_exp_f32_e32 v49, v48
	v_mul_f32_e32 v48, v144, v144
	v_fmamk_f32 v50, v48, 0xb94c1982, v180
	v_fmaak_f32 v50, v48, v50, 0xbe2aaa9d
	v_mul_f32_e32 v50, v48, v50
	v_fmac_f32_e32 v144, v144, v50
	v_fmamk_f32 v50, v48, 0x37d75334, v181
	v_fmaak_f32 v50, v48, v50, 0x3d2aabf7
	v_fmaak_f32 v50, v48, v50, 0xbf000004
	v_fma_f32 v48, v48, v50, 1.0
	v_cmp_eq_u32_e32 vcc, 0, v52
	v_lshlrev_b32_e32 v50, 30, v145
	v_xor_b32_e32 v53, v143, v142
	v_cndmask_b32_e32 v52, v48, v144, vcc
	v_and_b32_e32 v51, 0x80000000, v50
	v_xor_b32_e32 v52, v53, v52
	v_xor_b32_e32 v51, v52, v51
	v_xor_b32_e32 v52, 0x80000000, v144
	v_cndmask_b32_e32 v48, v52, v48, vcc
	v_bitop3_b32 v48, v48, v50, s14 bitop3:0x78
	v_cmp_class_f32_e64 vcc, v142, s10
	v_cvt_pk_bf16_f32 v70, v70, v166
	v_cvt_pk_bf16_f32 v76, v76, v165
	v_cndmask_b32_e32 v48, v191, v48, vcc
	v_cndmask_b32_e32 v50, v191, v51, vcc
	v_fma_f32 v48, v49, v48, -1.0
	v_mul_f32_e32 v49, v49, v50
	v_pk_mul_f32 v[50:51], v[102:103], v[102:103]
	v_cvt_pk_bf16_f32 v75, v75, v163
	v_add_f32_e32 v50, v50, v51
	v_div_scale_f32 v51, s[96:97], v50, v50, 1.0
	v_rcp_f32_e32 v52, v51
	v_cvt_pk_bf16_f32 v74, v74, v161
	v_cvt_pk_bf16_f32 v80, v80, v159
	v_cvt_pk_bf16_f32 v79, v79, v157
	v_fma_f32 v53, -v51, v52, 1.0
	v_fmac_f32_e32 v52, v53, v52
	v_div_scale_f32 v53, vcc, 1.0, v50, 1.0
	v_mul_f32_e32 v54, v53, v52
	v_fma_f32 v55, -v51, v54, v53
	v_fmac_f32_e32 v54, v55, v52
	v_fma_f32 v51, -v51, v54, v53
	v_div_fmas_f32 v51, v51, v52, v54
	v_mov_b32_e32 v52, v49
	v_mov_b32_e32 v53, v48
	v_div_fixup_f32 v54, v51, v50, 1.0
	v_pk_mul_f32 v[50:51], v[102:103], v[48:49]
	v_pk_mul_f32 v[48:49], v[102:103], v[52:53]
	v_add_f32_e32 v50, v50, v51
	v_sub_f32_e32 v48, v48, v49
	v_mul_f32_e32 v50, v54, v50
	v_mul_f32_e32 v48, v54, v48
	v_pk_mul_f32 v[52:53], v[44:45], v[50:51] op_sel_hi:[1,0]
	v_pk_mul_f32 v[44:45], v[44:45], v[48:49] op_sel_hi:[1,0]
	v_pk_fma_f32 v[52:53], v[40:41], v[48:49], v[52:53] op_sel_hi:[1,0,1]
	v_pk_fma_f32 v[40:41], v[40:41], v[50:51], v[44:45] op_sel_hi:[1,0,1] neg_lo:[0,0,1] neg_hi:[0,0,1]
	v_pk_mul_f32 v[44:45], v[46:47], v[48:49] op_sel_hi:[1,0]
	s_nop 0
	s_nop 0
	v_cvt_pk_bf16_f32 v102, v40, v41
	v_pk_mul_f32 v[40:41], v[46:47], v[50:51] op_sel_hi:[1,0]
	v_cvt_pk_bf16_f32 v78, v78, v156
	v_pk_fma_f32 v[40:41], v[42:43], v[48:49], v[40:41] op_sel_hi:[1,0,1]
	v_pk_fma_f32 v[42:43], v[42:43], v[50:51], v[44:45] op_sel_hi:[1,0,1] neg_lo:[0,0,1] neg_hi:[0,0,1]
	v_cvt_pk_bf16_f32 v84, v84, v154
	v_mov_b32_e32 v41, v43
	v_mov_b32_e32 v40, v42
	v_cvt_pk_bf16_f32 v103, v40, v41
	v_pk_mul_f32 v[40:41], v[36:37], v[50:51] op_sel_hi:[1,0]
	v_pk_mul_f32 v[36:37], v[36:37], v[48:49] op_sel_hi:[1,0]
	v_pk_fma_f32 v[40:41], v[32:33], v[48:49], v[40:41] op_sel_hi:[1,0,1]
	v_pk_fma_f32 v[32:33], v[32:33], v[50:51], v[36:37] op_sel_hi:[1,0,1] neg_lo:[0,0,1] neg_hi:[0,0,1]
	v_pk_mul_f32 v[36:37], v[48:49], v[38:39] op_sel_hi:[0,1]
	s_nop 0
	s_nop 0
	v_cvt_pk_bf16_f32 v104, v32, v33
	v_pk_mul_f32 v[32:33], v[50:51], v[38:39] op_sel_hi:[0,1]
	v_pk_fma_f32 v[32:33], v[34:35], v[48:49], v[32:33] op_sel_hi:[1,0,1]
	v_pk_fma_f32 v[34:35], v[34:35], v[50:51], v[36:37] op_sel_hi:[1,0,1] neg_lo:[0,0,1] neg_hi:[0,0,1]
	v_and_b32_e32 v36, 1, v117
	v_mov_b32_e32 v33, v35
	v_mov_b32_e32 v32, v34
	v_cvt_pk_bf16_f32 v105, v32, v33
	v_mul_f32_e32 v32, v110, v98
	v_mul_f32_e32 v32, 0x3fb8aa3b, v32
	v_exp_f32_e32 v33, v32
	v_mul_f32_e32 v32, v116, v116
	v_fmamk_f32 v34, v32, 0xb94c1982, v180
	v_fmaak_f32 v34, v32, v34, 0xbe2aaa9d
	v_mul_f32_e32 v34, v32, v34
	v_fmac_f32_e32 v116, v116, v34
	v_fmamk_f32 v34, v32, 0x37d75334, v181
	v_fmaak_f32 v34, v32, v34, 0x3d2aabf7
	v_fmaak_f32 v34, v32, v34, 0xbf000004
	v_fma_f32 v32, v32, v34, 1.0
	v_cmp_eq_u32_e32 vcc, 0, v36
	v_lshlrev_b32_e32 v34, 30, v117
	v_xor_b32_e32 v37, v109, v108
	v_cndmask_b32_e32 v36, v32, v116, vcc
	v_and_b32_e32 v35, 0x80000000, v34
	v_xor_b32_e32 v36, v37, v36
	v_xor_b32_e32 v35, v36, v35
	v_xor_b32_e32 v36, 0x80000000, v116
	v_cndmask_b32_e32 v32, v36, v32, vcc
	v_bitop3_b32 v32, v32, v34, s14 bitop3:0x78
	v_cmp_class_f32_e64 vcc, v108, s10
	v_cvt_pk_bf16_f32 v86, v86, v91
	v_cvt_pk_bf16_f32 v91, v69, v81
	v_cndmask_b32_e32 v32, v191, v32, vcc
	v_cndmask_b32_e32 v34, v191, v35, vcc
	v_fma_f32 v32, v33, v32, -1.0
	v_mul_f32_e32 v33, v33, v34
	v_pk_mul_f32 v[34:35], v[98:99], v[98:99]
	v_cvt_pk_bf16_f32 v90, v73, v77
	v_add_f32_e32 v34, v34, v35
	v_div_scale_f32 v35, s[96:97], v34, v34, 1.0
	v_rcp_f32_e32 v36, v35
	v_cvt_pk_bf16_f32 v93, v85, v93
	v_cvt_pk_bf16_f32 v85, v153, v155
	v_cvt_pk_bf16_f32 v81, v158, v160
	v_fma_f32 v37, -v35, v36, 1.0
	v_fmac_f32_e32 v36, v37, v36
	v_div_scale_f32 v37, vcc, 1.0, v34, 1.0
	v_mul_f32_e32 v38, v37, v36
	v_fma_f32 v39, -v35, v38, v37
	v_fmac_f32_e32 v38, v39, v36
	v_fma_f32 v35, -v35, v38, v37
	v_div_fmas_f32 v35, v35, v36, v38
	v_mov_b32_e32 v36, v33
	v_mov_b32_e32 v37, v32
	v_div_fixup_f32 v38, v35, v34, 1.0
	v_pk_mul_f32 v[34:35], v[98:99], v[32:33]
	v_pk_mul_f32 v[32:33], v[98:99], v[36:37]
	v_add_f32_e32 v34, v34, v35
	v_sub_f32_e32 v32, v32, v33
	v_mul_f32_e32 v34, v38, v34
	v_mul_f32_e32 v32, v38, v32
	v_pk_mul_f32 v[36:37], v[28:29], v[34:35] op_sel_hi:[1,0]
	v_pk_mul_f32 v[28:29], v[28:29], v[32:33] op_sel_hi:[1,0]
	v_pk_fma_f32 v[36:37], v[24:25], v[32:33], v[36:37] op_sel_hi:[1,0,1]
	v_pk_fma_f32 v[24:25], v[24:25], v[34:35], v[28:29] op_sel_hi:[1,0,1] neg_lo:[0,0,1] neg_hi:[0,0,1]
	v_pk_mul_f32 v[28:29], v[30:31], v[32:33] op_sel_hi:[1,0]
	v_mov_b32_e32 v25, v37
	v_mov_b32_e32 v24, v36
	v_cvt_pk_bf16_f32 v106, v24, v25
	v_pk_mul_f32 v[24:25], v[30:31], v[34:35] op_sel_hi:[1,0]
	v_cvt_pk_bf16_f32 v77, v162, v164
	v_pk_fma_f32 v[24:25], v[26:27], v[32:33], v[24:25] op_sel_hi:[1,0,1]
	v_pk_fma_f32 v[26:27], v[26:27], v[34:35], v[28:29] op_sel_hi:[1,0,1] neg_lo:[0,0,1] neg_hi:[0,0,1]
	v_cvt_pk_bf16_f32 v73, v167, v169
	s_nop 0
	s_nop 0
	v_cvt_pk_bf16_f32 v107, v24, v25
	v_pk_mul_f32 v[24:25], v[20:21], v[34:35] op_sel_hi:[1,0]
	v_pk_mul_f32 v[20:21], v[20:21], v[32:33] op_sel_hi:[1,0]
	v_pk_fma_f32 v[24:25], v[16:17], v[32:33], v[24:25] op_sel_hi:[1,0,1]
	v_pk_fma_f32 v[16:17], v[16:17], v[34:35], v[20:21] op_sel_hi:[1,0,1] neg_lo:[0,0,1] neg_hi:[0,0,1]
	v_pk_mul_f32 v[20:21], v[32:33], v[22:23] op_sel_hi:[0,1]
	v_mov_b32_e32 v17, v25
	v_mov_b32_e32 v16, v24
	v_cvt_pk_bf16_f32 v108, v16, v17
	v_pk_mul_f32 v[16:17], v[34:35], v[22:23] op_sel_hi:[0,1]
	v_pk_fma_f32 v[16:17], v[18:19], v[32:33], v[16:17] op_sel_hi:[1,0,1]
	v_pk_fma_f32 v[18:19], v[18:19], v[34:35], v[20:21] op_sel_hi:[1,0,1] neg_lo:[0,0,1] neg_hi:[0,0,1]
	v_and_b32_e32 v20, 1, v114
	s_nop 0
	s_nop 0
	v_cvt_pk_bf16_f32 v109, v16, v17
	v_mul_f32_e32 v16, v110, v60
	v_mul_f32_e32 v16, 0x3fb8aa3b, v16
	v_exp_f32_e32 v17, v16
	v_mul_f32_e32 v16, v113, v113
	v_fmamk_f32 v18, v16, 0xb94c1982, v180
	v_fmaak_f32 v18, v16, v18, 0xbe2aaa9d
	v_mul_f32_e32 v18, v16, v18
	v_fmac_f32_e32 v113, v113, v18
	v_fmamk_f32 v18, v16, 0x37d75334, v181
	v_fmaak_f32 v18, v16, v18, 0x3d2aabf7
	v_fmaak_f32 v18, v16, v18, 0xbf000004
	v_fma_f32 v16, v16, v18, 1.0
	v_cmp_eq_u32_e32 vcc, 0, v20
	v_lshlrev_b32_e32 v18, 30, v114
	v_xor_b32_e32 v21, v112, v111
	v_cndmask_b32_e32 v20, v16, v113, vcc
	v_and_b32_e32 v19, 0x80000000, v18
	v_xor_b32_e32 v20, v21, v20
	v_xor_b32_e32 v19, v20, v19
	v_xor_b32_e32 v20, 0x80000000, v113
	v_cndmask_b32_e32 v16, v20, v16, vcc
	v_bitop3_b32 v16, v16, v18, s14 bitop3:0x78
	v_cmp_class_f32_e64 vcc, v111, s10
	v_cvt_pk_bf16_f32 v69, v172, v174
	v_cvt_pk_bf16_f32 v65, v192, v193
	v_cndmask_b32_e32 v16, v191, v16, vcc
	v_cndmask_b32_e32 v18, v191, v19, vcc
	v_fma_f32 v16, v17, v16, -1.0
	v_mul_f32_e32 v17, v17, v18
	v_pk_mul_f32 v[18:19], v[60:61], v[60:61]
	s_nop 0
	v_add_f32_e32 v18, v18, v19
	v_div_scale_f32 v19, s[96:97], v18, v18, 1.0
	v_rcp_f32_e32 v20, v19
	s_nop 0
	v_fma_f32 v21, -v19, v20, 1.0
	v_fmac_f32_e32 v20, v21, v20
	v_div_scale_f32 v21, vcc, 1.0, v18, 1.0
	v_mul_f32_e32 v22, v21, v20
	v_fma_f32 v23, -v19, v22, v21
	v_fmac_f32_e32 v22, v23, v20
	v_fma_f32 v19, -v19, v22, v21
	v_div_fmas_f32 v19, v19, v20, v22
	v_mov_b32_e32 v20, v17
	v_mov_b32_e32 v21, v16
	v_div_fixup_f32 v22, v19, v18, 1.0
	v_pk_mul_f32 v[18:19], v[60:61], v[16:17]
	v_pk_mul_f32 v[16:17], v[60:61], v[20:21]
	v_add_f32_e32 v18, v18, v19
	v_sub_f32_e32 v16, v16, v17
	v_mul_f32_e32 v18, v22, v18
	v_mul_f32_e32 v16, v22, v16
	v_pk_mul_f32 v[20:21], v[12:13], v[18:19] op_sel_hi:[1,0]
	v_pk_mul_f32 v[12:13], v[12:13], v[16:17] op_sel_hi:[1,0]
	v_pk_fma_f32 v[20:21], v[8:9], v[16:17], v[20:21] op_sel_hi:[1,0,1]
	v_pk_fma_f32 v[8:9], v[8:9], v[18:19], v[12:13] op_sel_hi:[1,0,1] neg_lo:[0,0,1] neg_hi:[0,0,1]
	v_pk_mul_f32 v[12:13], v[14:15], v[16:17] op_sel_hi:[1,0]
	s_nop 0
	s_nop 0
	v_cvt_pk_bf16_f32 v110, v8, v9
	v_pk_mul_f32 v[8:9], v[14:15], v[18:19] op_sel_hi:[1,0]
	v_lshlrev_b32_e32 v60, 4, v140
	v_pk_fma_f32 v[8:9], v[10:11], v[16:17], v[8:9] op_sel_hi:[1,0,1]
	v_pk_fma_f32 v[10:11], v[10:11], v[18:19], v[12:13] op_sel_hi:[1,0,1] neg_lo:[0,0,1] neg_hi:[0,0,1]
	v_ashrrev_i32_e32 v61, 31, v60
	v_mov_b32_e32 v9, v11
	v_mov_b32_e32 v8, v10
	v_cvt_pk_bf16_f32 v111, v8, v9
	v_pk_mul_f32 v[8:9], v[4:5], v[18:19] op_sel_hi:[1,0]
	v_pk_mul_f32 v[4:5], v[4:5], v[16:17] op_sel_hi:[1,0]
	v_pk_fma_f32 v[8:9], v[0:1], v[16:17], v[8:9] op_sel_hi:[1,0,1]
	v_pk_fma_f32 v[0:1], v[0:1], v[18:19], v[4:5] op_sel_hi:[1,0,1] neg_lo:[0,0,1] neg_hi:[0,0,1]
	v_pk_mul_f32 v[4:5], v[16:17], v[6:7] op_sel_hi:[0,1]
	s_nop 0
	s_nop 0
	v_cvt_pk_bf16_f32 v112, v0, v1
	v_pk_mul_f32 v[0:1], v[18:19], v[6:7] op_sel_hi:[0,1]
	v_pk_fma_f32 v[0:1], v[2:3], v[16:17], v[0:1] op_sel_hi:[1,0,1]
	v_pk_fma_f32 v[2:3], v[2:3], v[18:19], v[4:5] op_sel_hi:[1,0,1] neg_lo:[0,0,1] neg_hi:[0,0,1]
	s_nop 0
	v_mov_b32_e32 v1, v3
	v_mov_b32_e32 v0, v2
	v_cvt_pk_bf16_f32 v113, v0, v1
	v_xor_b32_e32 v0, 0x80000000, v100
	v_cndmask_b32_e64 v0, v0, v149, s[46:47]
	v_bitop3_b32 v0, v0, v150, s14 bitop3:0x78
	s_lshl_b32 s46, s50, 12
	v_cndmask_b32_e64 v0, v191, v0, s[48:49]
	s_add_i32 s48, s46, 0x2000
	s_lshl_b32 s49, s50, 8
	s_and_b64 s[46:47], s[76:77], exec
	s_cselect_b32 s51, s48, s49
	s_cmp_eq_u32 s38, 0
	s_cselect_b64 s[46:47], -1, 0
	s_and_b64 vcc, s[46:47], exec
	s_mov_b32 s46, 0x27600000
	s_cselect_b32 s46, s46, 0x2c600000
	s_add_u32 s46, s58, s46
	v_mul_f32_e32 v150, v115, v0
	s_addc_u32 s47, s59, 0
	s_mov_b64 s[48:49], -1
	s_cbranch_vccnz .LBB0_622
	v_and_b32_e32 v56, 31, v133
	v_bfe_u32 v57, v133, 5, 1
	v_and_b32_e32 v58, 63, v133
	v_lshl_add_u32 v240, v58, 2, v127
	v_mul_u32_u24_e32 v59, 0x110, v56
	v_lshl_add_u32 v241, v57, 4, v127
	v_add_u32_e32 v241, v241, v59
	s_lshl_b32 s76, s39, 5
	s_add_i32 s76, s76, s51
	s_sub_i32 s76, s76, 32
	v_add_u32_e32 v242, s76, v56
	s_mov_b32 s48, 0xffff0000
	s_mov_b32 s49, -1
	v_mov_b32_e32 v243, 0
	v_lshlrev_b64 v[242:243], 11, v[242:243]
	v_lshlrev_b64 v[248:249], 1, v[60:61]
	v_lshl_add_u64 v[244:245], s[94:95], 0, v[242:243]
	v_lshl_add_u64 v[246:247], s[46:47], 0, v[242:243]
	v_lshl_add_u64 v[244:245], v[244:245], 0, v[248:249]
	v_lshl_add_u64 v[246:247], v[246:247], 0, v[248:249]
	v_lshlrev_b32_e32 v128, 4, v57
	v_lshl_add_u64 v[244:245], v[244:245], 0, v[128:129]
	v_lshlrev_b32_e32 v128, 3, v57
	v_lshl_add_u64 v[246:247], v[246:247], 0, v[128:129]
	global_load_dwordx4 v[48:51], v[244:245], off
	s_mov_b32 s77, 1
	s_mov_b32 s76, 0
	s_cmp_lt_u32 s77, s39
	s_cselect_b32 s46, s48, 0
	s_cselect_b32 s47, s49, 0
	s_add_i32 s77, s77, 1
	v_lshl_add_u64 v[244:245], v[244:245], 0, s[46:47]
	global_load_dwordx4 v[52:55], v[244:245], off
	v_mov_b32_e32 v174, v135
	v_mov_b32_e32 v252, v150
	v_mov_b32_e32 v175, v101
	s_waitcnt vmcnt(0)
	v_mfma_f32_32x32x16_bf16 v[0:15], v[48:51], v[110:113], 0
	v_mfma_f32_32x32x16_bf16 v[16:31], v[48:51], v[102:105], 0
	v_mfma_f32_32x32x16_bf16 v[32:47], v[48:51], v[106:109], 0
	v_mfma_f32_32x32x16_bf16 v[192:207], v[48:51], v[94:97], 0
	s_nop 15
	v_permlane32_swap_b32 v0, v16
	v_permlane32_swap_b32 v1, v17
	v_permlane32_swap_b32 v2, v18
	v_permlane32_swap_b32 v3, v19
	v_permlane32_swap_b32 v4, v20
	v_permlane32_swap_b32 v5, v21
	v_permlane32_swap_b32 v6, v22
	v_permlane32_swap_b32 v7, v23
	v_permlane32_swap_b32 v8, v24
	v_permlane32_swap_b32 v9, v25
	v_permlane32_swap_b32 v10, v26
	v_permlane32_swap_b32 v11, v27
	v_permlane32_swap_b32 v12, v28
	v_permlane32_swap_b32 v13, v29
	v_permlane32_swap_b32 v14, v30
	v_permlane32_swap_b32 v15, v31
	v_permlane32_swap_b32 v32, v192
	v_permlane32_swap_b32 v33, v193
	v_permlane32_swap_b32 v34, v194
	v_permlane32_swap_b32 v35, v195
	v_permlane32_swap_b32 v36, v196
	v_permlane32_swap_b32 v37, v197
	v_permlane32_swap_b32 v38, v198
	v_permlane32_swap_b32 v39, v199
	v_permlane32_swap_b32 v40, v200
	v_permlane32_swap_b32 v41, v201
	v_permlane32_swap_b32 v42, v202
	v_permlane32_swap_b32 v43, v203
	v_permlane32_swap_b32 v44, v204
	v_permlane32_swap_b32 v45, v205
	v_permlane32_swap_b32 v46, v206
	v_permlane32_swap_b32 v47, v207
	s_nop 1
.Lscr_loop:
	s_nop 1
	v_fma_f32 v31, -v131, v175, v31
	v_fma_f32 v207, v131, v174, v207
	v_fmac_f32_e32 v31, v252, v174
	v_fmac_f32_e32 v207, v252, v175
	v_cvt_pk_bf16_f32 v98, v31, v207
	ds_write_b32 v240, v98 offset:16624
	v_fma_f32 v30, -v131, v207, v30
	v_fma_f32 v206, v131, v31, v206
	v_fmac_f32_e32 v30, v252, v31
	v_fmac_f32_e32 v206, v252, v207
	v_cvt_pk_bf16_f32 v99, v30, v206
	ds_write_b32 v240, v99 offset:16352
	v_fma_f32 v29, -v131, v206, v29
	v_fma_f32 v205, v131, v30, v205
	v_fmac_f32_e32 v29, v252, v30
	v_fmac_f32_e32 v205, v252, v206
	v_cvt_pk_bf16_f32 v98, v29, v205
	ds_write_b32 v240, v98 offset:16080
	v_fma_f32 v28, -v131, v205, v28
	v_fma_f32 v204, v131, v29, v204
	v_fmac_f32_e32 v28, v252, v29
	v_fmac_f32_e32 v204, v252, v205
	v_cvt_pk_bf16_f32 v99, v28, v204
	ds_write_b32 v240, v99 offset:15808
	s_cmp_eq_u32 s76, 0
	s_cbranch_scc1 .Lscr_noy
	v_add_f32_e32 v56, v142, v158
	v_add_f32_e32 v57, v143, v159
	v_add_f32_e32 v58, v144, v160
	v_add_f32_e32 v59, v145, v161
	v_add_f32_e32 v116, v146, v162
	v_add_f32_e32 v117, v147, v163
	v_add_f32_e32 v250, v148, v164
	v_add_f32_e32 v251, v149, v165
	v_cvt_pk_bf16_f32 v56, v56, v57
	v_cvt_pk_bf16_f32 v57, v58, v59
	v_cvt_pk_bf16_f32 v58, v116, v117
	v_cvt_pk_bf16_f32 v59, v250, v251
	global_store_dwordx2 v[246:247], v[56:57], off
	global_store_dwordx2 v[246:247], v[58:59], off offset:16
	v_lshl_add_u64 v[246:247], v[246:247], 0, s[48:49]
.Lscr_noy:
	v_fma_f32 v15, -v131, v204, v15
	v_fma_f32 v47, v131, v28, v47
	v_fmac_f32_e32 v15, v252, v28
	v_fmac_f32_e32 v47, v252, v204
	v_cvt_pk_bf16_f32 v98, v15, v47
	ds_write_b32 v240, v98 offset:15536
	v_fma_f32 v14, -v131, v47, v14
	v_fma_f32 v46, v131, v15, v46
	v_fmac_f32_e32 v14, v252, v15
	v_fmac_f32_e32 v46, v252, v47
	v_cvt_pk_bf16_f32 v99, v14, v46
	ds_write_b32 v240, v99 offset:15264
	v_fma_f32 v13, -v131, v46, v13
	v_fma_f32 v45, v131, v14, v45
	v_fmac_f32_e32 v13, v252, v14
	v_fmac_f32_e32 v45, v252, v46
	v_cvt_pk_bf16_f32 v98, v13, v45
	ds_write_b32 v240, v98 offset:14992
	v_fma_f32 v12, -v131, v45, v12
	v_fma_f32 v44, v131, v13, v44
	v_fmac_f32_e32 v12, v252, v13
	v_fmac_f32_e32 v44, v252, v45
	v_cvt_pk_bf16_f32 v99, v12, v44
	ds_write_b32 v240, v99 offset:14720
	v_fma_f32 v27, -v131, v44, v27
	v_fma_f32 v203, v131, v12, v203
	v_fmac_f32_e32 v27, v252, v12
	v_fmac_f32_e32 v203, v252, v44
	v_cvt_pk_bf16_f32 v98, v27, v203
	ds_write_b32 v240, v98 offset:14448
	v_fma_f32 v26, -v131, v203, v26
	v_fma_f32 v202, v131, v27, v202
	v_fmac_f32_e32 v26, v252, v27
	v_fmac_f32_e32 v202, v252, v203
	v_cvt_pk_bf16_f32 v99, v26, v202
	ds_write_b32 v240, v99 offset:14176
	v_fma_f32 v25, -v131, v202, v25
	v_fma_f32 v201, v131, v26, v201
	v_fmac_f32_e32 v25, v252, v26
	v_fmac_f32_e32 v201, v252, v202
	v_cvt_pk_bf16_f32 v98, v25, v201
	ds_write_b32 v240, v98 offset:13904
	v_fma_f32 v24, -v131, v201, v24
	v_fma_f32 v200, v131, v25, v200
	v_fmac_f32_e32 v24, v252, v25
	v_fmac_f32_e32 v200, v252, v201
	v_cvt_pk_bf16_f32 v99, v24, v200
	ds_write_b32 v240, v99 offset:13632
	v_fma_f32 v11, -v131, v200, v11
	v_fma_f32 v43, v131, v24, v43
	v_fmac_f32_e32 v11, v252, v24
	v_fmac_f32_e32 v43, v252, v200
	v_cvt_pk_bf16_f32 v98, v11, v43
	ds_write_b32 v240, v98 offset:13360
	v_fma_f32 v10, -v131, v43, v10
	v_fma_f32 v42, v131, v11, v42
	v_fmac_f32_e32 v10, v252, v11
	v_fmac_f32_e32 v42, v252, v43
	v_cvt_pk_bf16_f32 v99, v10, v42
	ds_write_b32 v240, v99 offset:13088
	v_fma_f32 v9, -v131, v42, v9
	v_fma_f32 v41, v131, v10, v41
	v_fmac_f32_e32 v9, v252, v10
	v_fmac_f32_e32 v41, v252, v42
	v_cvt_pk_bf16_f32 v98, v9, v41
	ds_write_b32 v240, v98 offset:12816
	v_fma_f32 v8, -v131, v41, v8
	v_fma_f32 v40, v131, v9, v40
	v_fmac_f32_e32 v8, v252, v9
	v_fmac_f32_e32 v40, v252, v41
	v_cvt_pk_bf16_f32 v99, v8, v40
	ds_write_b32 v240, v99 offset:12544
	v_fma_f32 v23, -v131, v40, v23
	v_fma_f32 v199, v131, v8, v199
	v_fmac_f32_e32 v23, v252, v8
	v_fmac_f32_e32 v199, v252, v40
	v_cvt_pk_bf16_f32 v98, v23, v199
	ds_write_b32 v240, v98 offset:12272
	v_fma_f32 v22, -v131, v199, v22
	v_fma_f32 v198, v131, v23, v198
	v_fmac_f32_e32 v22, v252, v23
	v_fmac_f32_e32 v198, v252, v199
	v_cvt_pk_bf16_f32 v99, v22, v198
	ds_write_b32 v240, v99 offset:12000
	v_fma_f32 v21, -v131, v198, v21
	v_fma_f32 v197, v131, v22, v197
	v_fmac_f32_e32 v21, v252, v22
	v_fmac_f32_e32 v197, v252, v198
	v_cvt_pk_bf16_f32 v98, v21, v197
	ds_write_b32 v240, v98 offset:11728
	v_fma_f32 v20, -v131, v197, v20
	v_fma_f32 v196, v131, v21, v196
	v_fmac_f32_e32 v20, v252, v21
	v_fmac_f32_e32 v196, v252, v197
	v_cvt_pk_bf16_f32 v99, v20, v196
	ds_write_b32 v240, v99 offset:11456
	v_fma_f32 v7, -v131, v196, v7
	v_fma_f32 v39, v131, v20, v39
	v_fmac_f32_e32 v7, v252, v20
	v_fmac_f32_e32 v39, v252, v196
	v_cvt_pk_bf16_f32 v98, v7, v39
	ds_write_b32 v240, v98 offset:11184
	v_fma_f32 v6, -v131, v39, v6
	v_fma_f32 v38, v131, v7, v38
	v_fmac_f32_e32 v6, v252, v7
	v_fmac_f32_e32 v38, v252, v39
	v_cvt_pk_bf16_f32 v99, v6, v38
	ds_write_b32 v240, v99 offset:10912
	v_fma_f32 v5, -v131, v38, v5
	v_fma_f32 v37, v131, v6, v37
	v_fmac_f32_e32 v5, v252, v6
	v_fmac_f32_e32 v37, v252, v38
	v_cvt_pk_bf16_f32 v98, v5, v37
	ds_write_b32 v240, v98 offset:10640
	v_fma_f32 v4, -v131, v37, v4
	v_fma_f32 v36, v131, v5, v36
	v_fmac_f32_e32 v4, v252, v5
	v_fmac_f32_e32 v36, v252, v37
	v_cvt_pk_bf16_f32 v99, v4, v36
	ds_write_b32 v240, v99 offset:10368
	v_fma_f32 v19, -v131, v36, v19
	v_fma_f32 v195, v131, v4, v195
	v_fmac_f32_e32 v19, v252, v4
	v_fmac_f32_e32 v195, v252, v36
	v_cvt_pk_bf16_f32 v98, v19, v195
	ds_write_b32 v240, v98 offset:10096
	v_fma_f32 v18, -v131, v195, v18
	v_fma_f32 v194, v131, v19, v194
	v_fmac_f32_e32 v18, v252, v19
	v_fmac_f32_e32 v194, v252, v195
	v_cvt_pk_bf16_f32 v99, v18, v194
	ds_write_b32 v240, v99 offset:9824
	v_fma_f32 v17, -v131, v194, v17
	v_fma_f32 v193, v131, v18, v193
	v_fmac_f32_e32 v17, v252, v18
	v_fmac_f32_e32 v193, v252, v194
	v_cvt_pk_bf16_f32 v98, v17, v193
	ds_write_b32 v240, v98 offset:9552
	v_fma_f32 v16, -v131, v193, v16
	v_fma_f32 v192, v131, v17, v192
	v_fmac_f32_e32 v16, v252, v17
	v_fmac_f32_e32 v192, v252, v193
	v_cvt_pk_bf16_f32 v99, v16, v192
	ds_write_b32 v240, v99 offset:9280
	v_fma_f32 v3, -v131, v192, v3
	v_fma_f32 v35, v131, v16, v35
	v_fmac_f32_e32 v3, v252, v16
	v_fmac_f32_e32 v35, v252, v192
	v_cvt_pk_bf16_f32 v98, v3, v35
	ds_write_b32 v240, v98 offset:9008
	v_fma_f32 v2, -v131, v35, v2
	v_fma_f32 v34, v131, v3, v34
	v_fmac_f32_e32 v2, v252, v3
	v_fmac_f32_e32 v34, v252, v35
	v_cvt_pk_bf16_f32 v99, v2, v34
	ds_write_b32 v240, v99 offset:8736
	v_fma_f32 v1, -v131, v34, v1
	v_fma_f32 v33, v131, v2, v33
	v_fmac_f32_e32 v1, v252, v2
	v_fmac_f32_e32 v33, v252, v34
	v_cvt_pk_bf16_f32 v98, v1, v33
	ds_write_b32 v240, v98 offset:8464
	v_fma_f32 v174, -v131, v33, v0
	v_fma_f32 v175, v131, v1, v32
	v_fmac_f32_e32 v174, v252, v1
	v_fmac_f32_e32 v175, v252, v33
	v_cvt_pk_bf16_f32 v99, v174, v175
	ds_write_b32 v240, v99 offset:8192
	s_waitcnt vmcnt(2)
	v_mov_b64_e32 v[48:49], v[52:53]
	v_mov_b64_e32 v[50:51], v[54:55]
	s_cmp_lt_u32 s77, s39
	s_cselect_b32 s46, s48, 0
	s_cselect_b32 s47, s49, 0
	s_add_i32 s77, s77, 1
	v_lshl_add_u64 v[244:245], v[244:245], 0, s[46:47]
	global_load_dwordx4 v[52:55], v[244:245], off
	v_mfma_f32_32x32x16_bf16 v[0:15], v[48:51], v[110:113], 0
	v_mfma_f32_32x32x16_bf16 v[16:31], v[48:51], v[102:105], 0
	v_mfma_f32_32x32x16_bf16 v[32:47], v[48:51], v[106:109], 0
	v_mfma_f32_32x32x16_bf16 v[192:207], v[48:51], v[94:97], 0
	ds_read_b128 v[208:211], v241 offset:8192
	ds_read_b128 v[212:215], v241 offset:8224
	ds_read_b128 v[216:219], v241 offset:8256
	ds_read_b128 v[220:223], v241 offset:8288
	ds_read_b128 v[224:227], v241 offset:8320
	ds_read_b128 v[228:231], v241 offset:8352
	ds_read_b128 v[232:235], v241 offset:8384
	ds_read_b128 v[236:239], v241 offset:8416
	s_waitcnt lgkmcnt(7)
	v_mfma_f32_32x32x16_bf16 v[142:157], v[90:93], v[208:211], 0
	v_permlane32_swap_b32 v0, v16
	v_permlane32_swap_b32 v1, v17
	v_permlane32_swap_b32 v2, v18
	v_permlane32_swap_b32 v3, v19
	s_waitcnt lgkmcnt(6)
	v_mfma_f32_32x32x16_bf16 v[158:173], v[86:89], v[212:215], 0
	v_permlane32_swap_b32 v4, v20
	v_permlane32_swap_b32 v5, v21
	v_permlane32_swap_b32 v6, v22
	v_permlane32_swap_b32 v7, v23
	s_waitcnt lgkmcnt(5)
	v_mfma_f32_32x32x16_bf16 v[142:157], v[82:85], v[216:219], v[142:157]
	v_permlane32_swap_b32 v8, v24
	v_permlane32_swap_b32 v9, v25
	v_permlane32_swap_b32 v10, v26
	v_permlane32_swap_b32 v11, v27
	s_waitcnt lgkmcnt(4)
	v_mfma_f32_32x32x16_bf16 v[158:173], v[78:81], v[220:223], v[158:173]
	v_permlane32_swap_b32 v12, v28
	v_permlane32_swap_b32 v13, v29
	v_permlane32_swap_b32 v14, v30
	v_permlane32_swap_b32 v15, v31
	s_waitcnt lgkmcnt(3)
	v_mfma_f32_32x32x16_bf16 v[142:157], v[74:77], v[224:227], v[142:157]
	v_permlane32_swap_b32 v32, v192
	v_permlane32_swap_b32 v33, v193
	v_permlane32_swap_b32 v34, v194
	v_permlane32_swap_b32 v35, v195
	s_waitcnt lgkmcnt(2)
	v_mfma_f32_32x32x16_bf16 v[158:173], v[70:73], v[228:231], v[158:173]
	v_permlane32_swap_b32 v36, v196
	v_permlane32_swap_b32 v37, v197
	v_permlane32_swap_b32 v38, v198
	v_permlane32_swap_b32 v39, v199
	s_waitcnt lgkmcnt(1)
	v_mfma_f32_32x32x16_bf16 v[142:157], v[66:69], v[232:235], v[142:157]
	v_permlane32_swap_b32 v40, v200
	v_permlane32_swap_b32 v41, v201
	v_permlane32_swap_b32 v42, v202
	v_permlane32_swap_b32 v43, v203
	s_waitcnt lgkmcnt(0)
	v_mfma_f32_32x32x16_bf16 v[158:173], v[62:65], v[236:239], v[158:173]
	v_permlane32_swap_b32 v44, v204
	v_permlane32_swap_b32 v45, v205
	v_permlane32_swap_b32 v46, v206
	v_permlane32_swap_b32 v47, v207
	s_add_i32 s76, s76, 1
	s_cmp_lt_u32 s76, s39
	s_cbranch_scc1 .Lscr_loop
	s_nop 15
	v_add_f32_e32 v56, v142, v158
	v_add_f32_e32 v57, v143, v159
	v_add_f32_e32 v58, v144, v160
	v_add_f32_e32 v59, v145, v161
	v_add_f32_e32 v116, v146, v162
	v_add_f32_e32 v117, v147, v163
	v_add_f32_e32 v250, v148, v164
	v_add_f32_e32 v251, v149, v165
	v_cvt_pk_bf16_f32 v56, v56, v57
	v_cvt_pk_bf16_f32 v57, v58, v59
	v_cvt_pk_bf16_f32 v58, v116, v117
	v_cvt_pk_bf16_f32 v59, v250, v251
	global_store_dwordx2 v[246:247], v[56:57], off
	global_store_dwordx2 v[246:247], v[58:59], off offset:16
	v_lshl_add_u64 v[246:247], v[246:247], 0, s[48:49]
	v_mov_b32_e32 v114, v174
	v_mov_b32_e32 v115, v175
	s_branch .LBB0_629
.LBB0_622:
	s_and_b64 vcc, exec, s[48:49]
	s_cbranch_vccz .LBB0_630
	v_and_b32_e32 v56, 31, v133
	v_bfe_u32 v57, v133, 5, 1
	v_and_b32_e32 v58, 63, v133
	v_lshl_add_u32 v240, v58, 2, v127
	v_mul_u32_u24_e32 v59, 0x110, v56
	v_lshl_add_u32 v241, v57, 4, v127
	v_add_u32_e32 v241, v241, v59
	v_add_u32_e32 v242, s51, v56
	s_mov_b32 s48, 0x10000
	s_mov_b32 s49, 0
	v_mov_b32_e32 v243, 0
	v_lshlrev_b64 v[242:243], 11, v[242:243]
	v_lshlrev_b64 v[248:249], 1, v[60:61]
	v_lshl_add_u64 v[244:245], s[94:95], 0, v[242:243]
	v_lshl_add_u64 v[246:247], s[46:47], 0, v[242:243]
	v_lshl_add_u64 v[244:245], v[244:245], 0, v[248:249]
	v_lshl_add_u64 v[246:247], v[246:247], 0, v[248:249]
	v_lshlrev_b32_e32 v128, 4, v57
	v_lshl_add_u64 v[244:245], v[244:245], 0, v[128:129]
	v_lshlrev_b32_e32 v128, 3, v57
	v_lshl_add_u64 v[246:247], v[246:247], 0, v[128:129]
	global_load_dwordx4 v[48:51], v[244:245], off
	s_mov_b32 s77, 1
	s_mov_b32 s76, 0
	s_cmp_lt_u32 s77, s39
	s_cselect_b32 s46, s48, 0
	s_cselect_b32 s47, s49, 0
	s_add_i32 s77, s77, 1
	v_lshl_add_u64 v[244:245], v[244:245], 0, s[46:47]
	global_load_dwordx4 v[52:55], v[244:245], off
	v_mov_b32_e32 v174, v135
	v_mov_b32_e32 v252, v150
	v_mov_b32_e32 v175, v101
	s_waitcnt vmcnt(0)
	v_mfma_f32_32x32x16_bf16 v[0:15], v[48:51], v[110:113], 0
	v_mfma_f32_32x32x16_bf16 v[16:31], v[48:51], v[102:105], 0
	v_mfma_f32_32x32x16_bf16 v[32:47], v[48:51], v[106:109], 0
	v_mfma_f32_32x32x16_bf16 v[192:207], v[48:51], v[94:97], 0
	s_nop 15
	v_permlane32_swap_b32 v0, v16
	v_permlane32_swap_b32 v1, v17
	v_permlane32_swap_b32 v2, v18
	v_permlane32_swap_b32 v3, v19
	v_permlane32_swap_b32 v4, v20
	v_permlane32_swap_b32 v5, v21
	v_permlane32_swap_b32 v6, v22
	v_permlane32_swap_b32 v7, v23
	v_permlane32_swap_b32 v8, v24
	v_permlane32_swap_b32 v9, v25
	v_permlane32_swap_b32 v10, v26
	v_permlane32_swap_b32 v11, v27
	v_permlane32_swap_b32 v12, v28
	v_permlane32_swap_b32 v13, v29
	v_permlane32_swap_b32 v14, v30
	v_permlane32_swap_b32 v15, v31
	v_permlane32_swap_b32 v32, v192
	v_permlane32_swap_b32 v33, v193
	v_permlane32_swap_b32 v34, v194
	v_permlane32_swap_b32 v35, v195
	v_permlane32_swap_b32 v36, v196
	v_permlane32_swap_b32 v37, v197
	v_permlane32_swap_b32 v38, v198
	v_permlane32_swap_b32 v39, v199
	v_permlane32_swap_b32 v40, v200
	v_permlane32_swap_b32 v41, v201
	v_permlane32_swap_b32 v42, v202
	v_permlane32_swap_b32 v43, v203
	v_permlane32_swap_b32 v44, v204
	v_permlane32_swap_b32 v45, v205
	v_permlane32_swap_b32 v46, v206
	v_permlane32_swap_b32 v47, v207
	s_nop 1
.Lscf_loop:
	s_nop 1
	v_fma_f32 v0, -v131, v175, v0
	v_fma_f32 v32, v131, v174, v32
	v_fmac_f32_e32 v0, v252, v174
	v_fmac_f32_e32 v32, v252, v175
	v_cvt_pk_bf16_f32 v98, v0, v32
	ds_write_b32 v240, v98 offset:8192
	v_fma_f32 v1, -v131, v32, v1
	v_fma_f32 v33, v131, v0, v33
	v_fmac_f32_e32 v1, v252, v0
	v_fmac_f32_e32 v33, v252, v32
	v_cvt_pk_bf16_f32 v99, v1, v33
	ds_write_b32 v240, v99 offset:8464
	v_fma_f32 v2, -v131, v33, v2
	v_fma_f32 v34, v131, v1, v34
	v_fmac_f32_e32 v2, v252, v1
	v_fmac_f32_e32 v34, v252, v33
	v_cvt_pk_bf16_f32 v98, v2, v34
	ds_write_b32 v240, v98 offset:8736
	v_fma_f32 v3, -v131, v34, v3
	v_fma_f32 v35, v131, v2, v35
	v_fmac_f32_e32 v3, v252, v2
	v_fmac_f32_e32 v35, v252, v34
	v_cvt_pk_bf16_f32 v99, v3, v35
	ds_write_b32 v240, v99 offset:9008
	s_cmp_eq_u32 s76, 0
	s_cbranch_scc1 .Lscf_noy
	v_add_f32_e32 v56, v142, v158
	v_add_f32_e32 v57, v143, v159
	v_add_f32_e32 v58, v144, v160
	v_add_f32_e32 v59, v145, v161
	v_add_f32_e32 v116, v146, v162
	v_add_f32_e32 v117, v147, v163
	v_add_f32_e32 v250, v148, v164
	v_add_f32_e32 v251, v149, v165
	v_cvt_pk_bf16_f32 v56, v56, v57
	v_cvt_pk_bf16_f32 v57, v58, v59
	v_cvt_pk_bf16_f32 v58, v116, v117
	v_cvt_pk_bf16_f32 v59, v250, v251
	global_store_dwordx2 v[246:247], v[56:57], off
	global_store_dwordx2 v[246:247], v[58:59], off offset:16
	v_lshl_add_u64 v[246:247], v[246:247], 0, s[48:49]
.Lscf_noy:
	v_fma_f32 v16, -v131, v35, v16
	v_fma_f32 v192, v131, v3, v192
	v_fmac_f32_e32 v16, v252, v3
	v_fmac_f32_e32 v192, v252, v35
	v_cvt_pk_bf16_f32 v98, v16, v192
	ds_write_b32 v240, v98 offset:9280
	v_fma_f32 v17, -v131, v192, v17
	v_fma_f32 v193, v131, v16, v193
	v_fmac_f32_e32 v17, v252, v16
	v_fmac_f32_e32 v193, v252, v192
	v_cvt_pk_bf16_f32 v99, v17, v193
	ds_write_b32 v240, v99 offset:9552
	v_fma_f32 v18, -v131, v193, v18
	v_fma_f32 v194, v131, v17, v194
	v_fmac_f32_e32 v18, v252, v17
	v_fmac_f32_e32 v194, v252, v193
	v_cvt_pk_bf16_f32 v98, v18, v194
	ds_write_b32 v240, v98 offset:9824
	v_fma_f32 v19, -v131, v194, v19
	v_fma_f32 v195, v131, v18, v195
	v_fmac_f32_e32 v19, v252, v18
	v_fmac_f32_e32 v195, v252, v194
	v_cvt_pk_bf16_f32 v99, v19, v195
	ds_write_b32 v240, v99 offset:10096
	v_fma_f32 v4, -v131, v195, v4
	v_fma_f32 v36, v131, v19, v36
	v_fmac_f32_e32 v4, v252, v19
	v_fmac_f32_e32 v36, v252, v195
	v_cvt_pk_bf16_f32 v98, v4, v36
	ds_write_b32 v240, v98 offset:10368
	v_fma_f32 v5, -v131, v36, v5
	v_fma_f32 v37, v131, v4, v37
	v_fmac_f32_e32 v5, v252, v4
	v_fmac_f32_e32 v37, v252, v36
	v_cvt_pk_bf16_f32 v99, v5, v37
	ds_write_b32 v240, v99 offset:10640
	v_fma_f32 v6, -v131, v37, v6
	v_fma_f32 v38, v131, v5, v38
	v_fmac_f32_e32 v6, v252, v5
	v_fmac_f32_e32 v38, v252, v37
	v_cvt_pk_bf16_f32 v98, v6, v38
	ds_write_b32 v240, v98 offset:10912
	v_fma_f32 v7, -v131, v38, v7
	v_fma_f32 v39, v131, v6, v39
	v_fmac_f32_e32 v7, v252, v6
	v_fmac_f32_e32 v39, v252, v38
	v_cvt_pk_bf16_f32 v99, v7, v39
	ds_write_b32 v240, v99 offset:11184
	v_fma_f32 v20, -v131, v39, v20
	v_fma_f32 v196, v131, v7, v196
	v_fmac_f32_e32 v20, v252, v7
	v_fmac_f32_e32 v196, v252, v39
	v_cvt_pk_bf16_f32 v98, v20, v196
	ds_write_b32 v240, v98 offset:11456
	v_fma_f32 v21, -v131, v196, v21
	v_fma_f32 v197, v131, v20, v197
	v_fmac_f32_e32 v21, v252, v20
	v_fmac_f32_e32 v197, v252, v196
	v_cvt_pk_bf16_f32 v99, v21, v197
	ds_write_b32 v240, v99 offset:11728
	v_fma_f32 v22, -v131, v197, v22
	v_fma_f32 v198, v131, v21, v198
	v_fmac_f32_e32 v22, v252, v21
	v_fmac_f32_e32 v198, v252, v197
	v_cvt_pk_bf16_f32 v98, v22, v198
	ds_write_b32 v240, v98 offset:12000
	v_fma_f32 v23, -v131, v198, v23
	v_fma_f32 v199, v131, v22, v199
	v_fmac_f32_e32 v23, v252, v22
	v_fmac_f32_e32 v199, v252, v198
	v_cvt_pk_bf16_f32 v99, v23, v199
	ds_write_b32 v240, v99 offset:12272
	v_fma_f32 v8, -v131, v199, v8
	v_fma_f32 v40, v131, v23, v40
	v_fmac_f32_e32 v8, v252, v23
	v_fmac_f32_e32 v40, v252, v199
	v_cvt_pk_bf16_f32 v98, v8, v40
	ds_write_b32 v240, v98 offset:12544
	v_fma_f32 v9, -v131, v40, v9
	v_fma_f32 v41, v131, v8, v41
	v_fmac_f32_e32 v9, v252, v8
	v_fmac_f32_e32 v41, v252, v40
	v_cvt_pk_bf16_f32 v99, v9, v41
	ds_write_b32 v240, v99 offset:12816
	v_fma_f32 v10, -v131, v41, v10
	v_fma_f32 v42, v131, v9, v42
	v_fmac_f32_e32 v10, v252, v9
	v_fmac_f32_e32 v42, v252, v41
	v_cvt_pk_bf16_f32 v98, v10, v42
	ds_write_b32 v240, v98 offset:13088
	v_fma_f32 v11, -v131, v42, v11
	v_fma_f32 v43, v131, v10, v43
	v_fmac_f32_e32 v11, v252, v10
	v_fmac_f32_e32 v43, v252, v42
	v_cvt_pk_bf16_f32 v99, v11, v43
	ds_write_b32 v240, v99 offset:13360
	v_fma_f32 v24, -v131, v43, v24
	v_fma_f32 v200, v131, v11, v200
	v_fmac_f32_e32 v24, v252, v11
	v_fmac_f32_e32 v200, v252, v43
	v_cvt_pk_bf16_f32 v98, v24, v200
	ds_write_b32 v240, v98 offset:13632
	v_fma_f32 v25, -v131, v200, v25
	v_fma_f32 v201, v131, v24, v201
	v_fmac_f32_e32 v25, v252, v24
	v_fmac_f32_e32 v201, v252, v200
	v_cvt_pk_bf16_f32 v99, v25, v201
	ds_write_b32 v240, v99 offset:13904
	v_fma_f32 v26, -v131, v201, v26
	v_fma_f32 v202, v131, v25, v202
	v_fmac_f32_e32 v26, v252, v25
	v_fmac_f32_e32 v202, v252, v201
	v_cvt_pk_bf16_f32 v98, v26, v202
	ds_write_b32 v240, v98 offset:14176
	v_fma_f32 v27, -v131, v202, v27
	v_fma_f32 v203, v131, v26, v203
	v_fmac_f32_e32 v27, v252, v26
	v_fmac_f32_e32 v203, v252, v202
	v_cvt_pk_bf16_f32 v99, v27, v203
	ds_write_b32 v240, v99 offset:14448
	v_fma_f32 v12, -v131, v203, v12
	v_fma_f32 v44, v131, v27, v44
	v_fmac_f32_e32 v12, v252, v27
	v_fmac_f32_e32 v44, v252, v203
	v_cvt_pk_bf16_f32 v98, v12, v44
	ds_write_b32 v240, v98 offset:14720
	v_fma_f32 v13, -v131, v44, v13
	v_fma_f32 v45, v131, v12, v45
	v_fmac_f32_e32 v13, v252, v12
	v_fmac_f32_e32 v45, v252, v44
	v_cvt_pk_bf16_f32 v99, v13, v45
	ds_write_b32 v240, v99 offset:14992
	v_fma_f32 v14, -v131, v45, v14
	v_fma_f32 v46, v131, v13, v46
	v_fmac_f32_e32 v14, v252, v13
	v_fmac_f32_e32 v46, v252, v45
	v_cvt_pk_bf16_f32 v98, v14, v46
	ds_write_b32 v240, v98 offset:15264
	v_fma_f32 v15, -v131, v46, v15
	v_fma_f32 v47, v131, v14, v47
	v_fmac_f32_e32 v15, v252, v14
	v_fmac_f32_e32 v47, v252, v46
	v_cvt_pk_bf16_f32 v99, v15, v47
	ds_write_b32 v240, v99 offset:15536
	v_fma_f32 v28, -v131, v47, v28
	v_fma_f32 v204, v131, v15, v204
	v_fmac_f32_e32 v28, v252, v15
	v_fmac_f32_e32 v204, v252, v47
	v_cvt_pk_bf16_f32 v98, v28, v204
	ds_write_b32 v240, v98 offset:15808
	v_fma_f32 v29, -v131, v204, v29
	v_fma_f32 v205, v131, v28, v205
	v_fmac_f32_e32 v29, v252, v28
	v_fmac_f32_e32 v205, v252, v204
	v_cvt_pk_bf16_f32 v99, v29, v205
	ds_write_b32 v240, v99 offset:16080
	v_fma_f32 v30, -v131, v205, v30
	v_fma_f32 v206, v131, v29, v206
	v_fmac_f32_e32 v30, v252, v29
	v_fmac_f32_e32 v206, v252, v205
	v_cvt_pk_bf16_f32 v98, v30, v206
	ds_write_b32 v240, v98 offset:16352
	v_fma_f32 v174, -v131, v206, v31
	v_fma_f32 v175, v131, v30, v207
	v_fmac_f32_e32 v174, v252, v30
	v_fmac_f32_e32 v175, v252, v206
	v_cvt_pk_bf16_f32 v99, v174, v175
	ds_write_b32 v240, v99 offset:16624
	s_waitcnt vmcnt(2)
	v_mov_b64_e32 v[48:49], v[52:53]
	v_mov_b64_e32 v[50:51], v[54:55]
	s_cmp_lt_u32 s77, s39
	s_cselect_b32 s46, s48, 0
	s_cselect_b32 s47, s49, 0
	s_add_i32 s77, s77, 1
	v_lshl_add_u64 v[244:245], v[244:245], 0, s[46:47]
	global_load_dwordx4 v[52:55], v[244:245], off
	v_mfma_f32_32x32x16_bf16 v[0:15], v[48:51], v[110:113], 0
	v_mfma_f32_32x32x16_bf16 v[16:31], v[48:51], v[102:105], 0
	v_mfma_f32_32x32x16_bf16 v[32:47], v[48:51], v[106:109], 0
	v_mfma_f32_32x32x16_bf16 v[192:207], v[48:51], v[94:97], 0
	ds_read_b128 v[208:211], v241 offset:8192
	ds_read_b128 v[212:215], v241 offset:8224
	ds_read_b128 v[216:219], v241 offset:8256
	ds_read_b128 v[220:223], v241 offset:8288
	ds_read_b128 v[224:227], v241 offset:8320
	ds_read_b128 v[228:231], v241 offset:8352
	ds_read_b128 v[232:235], v241 offset:8384
	ds_read_b128 v[236:239], v241 offset:8416
	s_waitcnt lgkmcnt(7)
	v_mfma_f32_32x32x16_bf16 v[142:157], v[90:93], v[208:211], 0
	v_permlane32_swap_b32 v0, v16
	v_permlane32_swap_b32 v1, v17
	v_permlane32_swap_b32 v2, v18
	v_permlane32_swap_b32 v3, v19
	s_waitcnt lgkmcnt(6)
	v_mfma_f32_32x32x16_bf16 v[158:173], v[86:89], v[212:215], 0
	v_permlane32_swap_b32 v4, v20
	v_permlane32_swap_b32 v5, v21
	v_permlane32_swap_b32 v6, v22
	v_permlane32_swap_b32 v7, v23
	s_waitcnt lgkmcnt(5)
	v_mfma_f32_32x32x16_bf16 v[142:157], v[82:85], v[216:219], v[142:157]
	v_permlane32_swap_b32 v8, v24
	v_permlane32_swap_b32 v9, v25
	v_permlane32_swap_b32 v10, v26
	v_permlane32_swap_b32 v11, v27
	s_waitcnt lgkmcnt(4)
	v_mfma_f32_32x32x16_bf16 v[158:173], v[78:81], v[220:223], v[158:173]
	v_permlane32_swap_b32 v12, v28
	v_permlane32_swap_b32 v13, v29
	v_permlane32_swap_b32 v14, v30
	v_permlane32_swap_b32 v15, v31
	s_waitcnt lgkmcnt(3)
	v_mfma_f32_32x32x16_bf16 v[142:157], v[74:77], v[224:227], v[142:157]
	v_permlane32_swap_b32 v32, v192
	v_permlane32_swap_b32 v33, v193
	v_permlane32_swap_b32 v34, v194
	v_permlane32_swap_b32 v35, v195
	s_waitcnt lgkmcnt(2)
	v_mfma_f32_32x32x16_bf16 v[158:173], v[70:73], v[228:231], v[158:173]
	v_permlane32_swap_b32 v36, v196
	v_permlane32_swap_b32 v37, v197
	v_permlane32_swap_b32 v38, v198
	v_permlane32_swap_b32 v39, v199
	s_waitcnt lgkmcnt(1)
	v_mfma_f32_32x32x16_bf16 v[142:157], v[66:69], v[232:235], v[142:157]
	v_permlane32_swap_b32 v40, v200
	v_permlane32_swap_b32 v41, v201
	v_permlane32_swap_b32 v42, v202
	v_permlane32_swap_b32 v43, v203
	s_waitcnt lgkmcnt(0)
	v_mfma_f32_32x32x16_bf16 v[158:173], v[62:65], v[236:239], v[158:173]
	v_permlane32_swap_b32 v44, v204
	v_permlane32_swap_b32 v45, v205
	v_permlane32_swap_b32 v46, v206
	v_permlane32_swap_b32 v47, v207
	s_add_i32 s76, s76, 1
	s_cmp_lt_u32 s76, s39
	s_cbranch_scc1 .Lscf_loop
	s_nop 15
	v_add_f32_e32 v56, v142, v158
	v_add_f32_e32 v57, v143, v159
	v_add_f32_e32 v58, v144, v160
	v_add_f32_e32 v59, v145, v161
	v_add_f32_e32 v116, v146, v162
	v_add_f32_e32 v117, v147, v163
	v_add_f32_e32 v250, v148, v164
	v_add_f32_e32 v251, v149, v165
	v_cvt_pk_bf16_f32 v56, v56, v57
	v_cvt_pk_bf16_f32 v57, v58, v59
	v_cvt_pk_bf16_f32 v58, v116, v117
	v_cvt_pk_bf16_f32 v59, v250, v251
	global_store_dwordx2 v[246:247], v[56:57], off
	global_store_dwordx2 v[246:247], v[58:59], off offset:16
	v_lshl_add_u64 v[246:247], v[246:247], 0, s[48:49]
	v_mov_b32_e32 v135, v174
	v_mov_b32_e32 v101, v175
	s_branch .LBB0_631
